# ds_bpermute round trips replaced by v_permlane32_swap (MLA row max, sb stick sums) and DPP row reductions (residual epilogue ssq)
# speedup vs baseline: 1.0232x; 1.0023x over previous
; DI f32x16 mfma32(bf16x8 a, bf16x8 b, f32x16 c) { return __builtin_amdgcn_mfma_f32_32x32x16_bf16(a, b, c, 0, 0, 0); }
; DI void sb_attn_item(PP p, int item) {
;     ...
;         float gs[4], pg[4];
; #pragma unroll
;         for (int q = 0; q < 4; ++q) { gs[q] = (l1[4 * q] + l1[4 * q + 1]) + (l1[4 * q + 2] + l1[4 * q + 3]); pg[q] = __shfl_xor(gs[q], 32); }
;         float suf[4]; suf[3] = 0.f;
; #pragma unroll
;         for (int q = 2; q >= 0; --q) suf[q] = suf[q + 1] + gs[q + 1] + pg[q + 1];
;         f32x16 wv;
; #pragma unroll
;         for (int q = 0; q < 4; ++q) {
;             const float after = carry + suf[q] + (hh == 0 ? pg[q] : 0.f);
;             float cum = after;
; #pragma unroll
;             for (int e = 3; e >= 0; --e) {
;                 const int r = 4 * q + e;
;                 cum += l1[r];
;                 const float wgt = __builtin_amdgcn_exp2f(z[r] + cum);
;                 wv[r] = ((mbits >> r) & 1u) ? wgt : 0.f;
;             }
;         }
;         carry += suf[0] + gs[0] + pg[0];
; #pragma unroll
;         for (int ks = 0; ks < 2; ++ks) {
;             const bf16x8 pb = pack_step(wv, ks);
; #pragma unroll
;             for (int dvb = 0; dvb < 2; ++dvb) {
;                 const bf16_t* vq = vbase + (size_t)dvb * 32 * LSEQ + kt * 32 + 16 * ks;
;                 o[dvb] = mfma32(ld8x2(vq, vq + 8), pb, o[dvb]);
;             }
;         }
;         if (__all(carry < -60.f)) break;
.LBB0_230:
	s_or_b64 exec, exec, s[8:9]
	v_add_f32_e32 v160, v51, v50
	v_add_f32_e32 v161, v56, v61
	v_add_f32_e32 v162, v53, v52
	v_add_f32_e32 v163, v58, v57
	v_add_f32_e32 v164, v55, v54
	v_add_f32_e32 v165, v60, v59
	v_add_f32_e32 v166, v1, v62
	v_add_f32_e32 v167, v64, v63
	v_add_f32_e32 v160, v160, v161
	v_add_f32_e32 v162, v162, v163
	v_add_f32_e32 v164, v164, v165
	v_add_f32_e32 v92, v166, v167
	v_mov_b32_e32 v161, v160
	v_mov_b32_e32 v163, v160
	v_mov_b32_e32 v165, v162
	v_mov_b32_e32 v167, v162
	v_mov_b32_e32 v168, v164
	v_mov_b32_e32 v169, v164
	v_mov_b32_e32 v170, v92
	v_mov_b32_e32 v171, v92
	s_nop 1
	v_permlane32_swap_b32_e32 v161, v163
	v_permlane32_swap_b32_e32 v165, v167
	v_permlane32_swap_b32_e32 v168, v169
	v_permlane32_swap_b32_e32 v170, v171
	s_nop 0
	v_cndmask_b32_e32 v99, v161, v163, vcc
	v_cndmask_b32_e32 v101, v165, v167, vcc
	v_cndmask_b32_e32 v103, v168, v169, vcc
	v_cndmask_b32_e32 v94, v170, v171, vcc
	v_add_f32_e32 v97, 0, v160
	v_add_f32_e32 v97, v97, v99
	v_add_f32_e32 v95, v162, v97
	v_add_f32_e32 v95, v95, v101
	v_add_f32_e32 v93, v164, v95
	v_add_f32_e32 v93, v93, v103
	v_add_f32_e32 v96, v109, v93
	v_cndmask_b32_e32 v98, 0, v94, vcc
	v_add_f32_e32 v96, v98, v96
	v_add_f32_e32 v63, v63, v96
	v_add_f32_e32 v37, v37, v63
	v_add_f32_e32 v63, v64, v63
	v_exp_f32_e32 v37, v37
	v_add_f32_e32 v36, v36, v63
	v_add_f32_e32 v1, v1, v63
	v_exp_f32_e32 v36, v36
	v_add_f32_e32 v35, v35, v1
	v_add_f32_e32 v1, v62, v1
	v_and_b32_e32 v96, 8, v112
	v_exp_f32_e32 v35, v35
	v_add_f32_e32 v1, v34, v1
	v_cmp_ne_u32_e64 s[0:1], 0, v96
	v_and_b32_e32 v64, 4, v112
	v_exp_f32_e32 v1, v1
	v_cndmask_b32_e64 v37, 0, v37, s[0:1]
	v_cmp_ne_u32_e64 s[0:1], 0, v64
	v_and_b32_e32 v63, 2, v112
	v_and_b32_e32 v34, 1, v112
	v_cndmask_b32_e64 v36, 0, v36, s[0:1]
	v_cmp_ne_u32_e64 s[0:1], 0, v63
	v_cndmask_b32_e32 v62, 0, v103, vcc
	s_nop 0
	v_cndmask_b32_e64 v35, 0, v35, s[0:1]
	v_cmp_eq_u32_e64 s[0:1], 1, v34
	s_nop 1
	v_cndmask_b32_e64 v34, 0, v1, s[0:1]
	v_add_f32_e32 v1, v109, v95
	v_add_f32_e32 v1, v62, v1
	v_add_f32_e32 v1, v59, v1
	v_add_f32_e32 v41, v41, v1
	v_add_f32_e32 v1, v60, v1
	v_exp_f32_e32 v41, v41
	v_add_f32_e32 v40, v40, v1
	v_add_f32_e32 v1, v55, v1
	v_exp_f32_e32 v40, v40
	v_add_f32_e32 v39, v39, v1
	v_add_f32_e32 v1, v54, v1
	v_and_b32_e32 v59, 0x80, v112
	v_exp_f32_e32 v39, v39
	v_add_f32_e32 v1, v38, v1
	v_cmp_ne_u32_e64 s[0:1], 0, v59
	v_and_b32_e32 v59, 64, v112
	v_exp_f32_e32 v1, v1
	v_cndmask_b32_e64 v41, 0, v41, s[0:1]
	v_cmp_ne_u32_e64 s[0:1], 0, v59
	v_and_b32_e32 v55, 32, v112
	v_and_b32_e32 v38, 16, v112
	v_cndmask_b32_e64 v40, 0, v40, s[0:1]
	v_cmp_ne_u32_e64 s[0:1], 0, v55
	v_cndmask_b32_e32 v54, 0, v101, vcc
	v_cvt_pk_bf16_f32 v34, v34, v35
	v_cndmask_b32_e64 v39, 0, v39, s[0:1]
	v_cmp_ne_u32_e64 s[0:1], 0, v38
	v_cvt_pk_bf16_f32 v35, v36, v37
	v_cvt_pk_bf16_f32 v37, v40, v41
	v_cndmask_b32_e64 v38, 0, v1, s[0:1]
	v_add_f32_e32 v1, v109, v97
	v_add_f32_e32 v1, v54, v1
	v_add_f32_e32 v1, v57, v1
	v_add_f32_e32 v45, v45, v1
	v_exp_f32_e32 v45, v45
	v_add_f32_e32 v1, v58, v1
	v_add_f32_e32 v44, v44, v1
	v_and_b32_e32 v54, 0x800, v112
	v_exp_f32_e32 v44, v44
	v_add_f32_e32 v1, v53, v1
	v_cmp_ne_u32_e64 s[0:1], 0, v54
	v_add_f32_e32 v43, v43, v1
	v_add_f32_e32 v1, v52, v1
	v_cndmask_b32_e64 v54, 0, v45, s[0:1]
	v_and_b32_e32 v45, 0x400, v112
	v_exp_f32_e32 v43, v43
	v_add_f32_e32 v1, v42, v1
	v_cmp_ne_u32_e64 s[0:1], 0, v45
	v_exp_f32_e32 v1, v1
	v_and_b32_e32 v42, 0x100, v112
	v_cndmask_b32_e64 v55, 0, v44, s[0:1]
	v_and_b32_e32 v44, 0x200, v112
	v_cmp_ne_u32_e64 s[0:1], 0, v44
	v_cvt_pk_bf16_f32 v36, v38, v39
	s_nop 0
	v_cndmask_b32_e64 v53, 0, v43, s[0:1]
	v_cmp_ne_u32_e64 s[0:1], 0, v42
	v_cndmask_b32_e32 v42, 0, v99, vcc
	v_and_b32_e32 v43, 0x8000, v112
	v_cndmask_b32_e64 v52, 0, v1, s[0:1]
	v_add_f32_e32 v1, 0, v109
	v_add_f32_e32 v1, v1, v42
	v_add_f32_e32 v1, v61, v1
	v_add_f32_e32 v42, v49, v1
	v_exp_f32_e32 v42, v42
	v_cmp_ne_u32_e64 s[0:1], 0, v43
	v_add_f32_e32 v1, v56, v1
	v_and_b32_e32 v43, 0x4000, v112
	v_cndmask_b32_e64 v49, 0, v42, s[0:1]
	v_add_f32_e32 v42, v48, v1
	v_exp_f32_e32 v42, v42
	v_cmp_ne_u32_e64 s[0:1], 0, v43
	v_add_f32_e32 v1, v51, v1
	v_and_b32_e32 v43, 0x2000, v112
	v_cndmask_b32_e64 v48, 0, v42, s[0:1]
	v_add_f32_e32 v42, v47, v1
	v_exp_f32_e32 v42, v42
	v_cmp_ne_u32_e64 s[0:1], 0, v43
	v_add_f32_e32 v1, v50, v1
	v_add_f32_e32 v1, v46, v1
	v_cndmask_b32_e64 v47, 0, v42, s[0:1]
	v_and_b32_e32 v42, 0x1000, v112
	v_cmp_ne_u32_e64 s[0:1], 0, v42
	v_exp_f32_e32 v1, v1
	v_subrev_u32_e32 v196, 32, v196
	s_waitcnt vmcnt(0)
	v_mfma_f32_32x32x16_bf16 v[18:33], v[136:139], v[34:37], v[18:33]
	v_cndmask_b32_e64 v46, 0, v1, s[0:1]
	v_add_f32_e32 v1, v92, v93
	v_mfma_f32_32x32x16_bf16 v[2:17], v[140:143], v[34:37], v[2:17]
	v_cvt_pk_bf16_f32 v34, v52, v53
	v_cvt_pk_bf16_f32 v35, v55, v54
	v_cvt_pk_bf16_f32 v36, v46, v47
	v_cvt_pk_bf16_f32 v37, v48, v49
	v_add_f32_e32 v1, v1, v94
	v_add_f32_e32 v109, v109, v1
	v_mfma_f32_32x32x16_bf16 v[18:33], v[144:147], v[34:37], v[18:33]
	s_mov_b32 s0, 0xc2700000
	v_cmp_gt_f32_e64 s[0:1], s0, v109
	s_cmp_eq_u64 s[0:1], exec
	s_cselect_b64 s[2:3], -1, 0
	v_cmp_gt_u32_e64 s[0:1], 4, v111
	s_or_b64 s[0:1], s[2:3], s[0:1]
	v_mfma_f32_32x32x16_bf16 v[2:17], v[148:151], v[34:37], v[2:17]
	s_and_b64 s[0:1], exec, s[0:1]
	s_or_b64 s[6:7], s[0:1], s[6:7]
	s_andn2_b64 exec, exec, s[6:7]
	s_cbranch_execz .LBB0_233

; DI void mla2_item(PP p, int item, unsigned char* lds) {
;     ...
;                 float mx = fmaxf(fmaxf(sc[0][0], sc[1][0]), fmaxf(sc[2][0], sc[3][0]));
; #pragma unroll
;                 for (int r = 1; r < 16; ++r) mx = fmaxf(mx, fmaxf(fmaxf(sc[0][r], sc[1][r]), fmaxf(sc[2][r], sc[3][r])));
;                 mx = fmaxf(mx, __shfl_xor(mx, 32));
;                 const float mnew = fmaxf(mrun, mx);
;                 const float alpha = __builtin_amdgcn_exp2f(mrun - mnew);
;                 float rsum = 0.f;
; #pragma unroll
;                 for (int kb = 0; kb < 4; ++kb)
; #pragma unroll
;                     for (int r = 0; r < 16; ++r) { sc[kb][r] = __builtin_amdgcn_exp2f(sc[kb][r] - mnew); rsum += sc[kb][r]; }
;                 const bool grew = mnew > mrun;
;                 lrun = lrun * alpha + rsum; mrun = mnew;
;                 if (__any(grew)) { o[0] = o[0] * alpha; o[1] = o[1] * alpha; }
.LBB0_250:
	s_or_b64 exec, exec, s[70:71]
	s_nop 3
	v_max3_f32 v1, v48, v49, v50
	v_max3_f32 v2, v80, v81, v82
	v_max3_f32 v3, v96, v97, v98
	v_max3_f32 v4, v64, v65, v66
	v_max3_f32 v1, v1, v51, v52
	v_max3_f32 v2, v2, v83, v84
	v_max3_f32 v3, v3, v99, v100
	v_max3_f32 v4, v4, v67, v68
	v_max3_f32 v1, v1, v53, v54
	v_max3_f32 v2, v2, v85, v86
	v_max3_f32 v3, v3, v101, v102
	v_max3_f32 v4, v4, v69, v70
	v_max3_f32 v1, v1, v55, v56
	v_max3_f32 v2, v2, v87, v88
	v_max3_f32 v3, v3, v103, v104
	v_max3_f32 v4, v4, v71, v72
	v_max3_f32 v1, v1, v57, v58
	v_max3_f32 v2, v2, v89, v90
	v_max3_f32 v3, v3, v105, v106
	v_max3_f32 v4, v4, v73, v74
	v_max3_f32 v1, v1, v59, v60
	v_max3_f32 v2, v2, v91, v92
	v_max3_f32 v3, v3, v107, v108
	v_max3_f32 v4, v4, v75, v76
	v_max3_f32 v1, v1, v61, v62
	v_max3_f32 v2, v2, v93, v94
	v_max3_f32 v3, v3, v109, v110
	v_max3_f32 v4, v4, v77, v78
	v_max_f32_e32 v1, v1, v63
	v_max_f32_e32 v2, v2, v95
	v_max_f32_e32 v3, v3, v111
	v_max_f32_e32 v4, v4, v79
	v_max3_f32 v1, v1, v2, v3
	v_max_f32_e32 v1, v1, v4
	v_mov_b32_e32 v2, v1
	s_nop 1
	v_permlane32_swap_b32_e32 v2, v1
	s_nop 0
	v_max3_f32 v1, v238, v1, v2
	v_sub_f32_e32 v2, v238, v1
	v_exp_f32_e32 v2, v2
	v_cmp_gt_f32_e32 vcc, v1, v238
	s_cbranch_vccz .LBB0_252
	v_pk_mul_f32 v[46:47], v[46:47], v[2:3] op_sel_hi:[1,0]
	v_pk_mul_f32 v[44:45], v[44:45], v[2:3] op_sel_hi:[1,0]
	v_pk_mul_f32 v[42:43], v[42:43], v[2:3] op_sel_hi:[1,0]
	v_pk_mul_f32 v[40:41], v[40:41], v[2:3] op_sel_hi:[1,0]
	v_pk_mul_f32 v[38:39], v[38:39], v[2:3] op_sel_hi:[1,0]
	v_pk_mul_f32 v[36:37], v[36:37], v[2:3] op_sel_hi:[1,0]
	v_pk_mul_f32 v[34:35], v[34:35], v[2:3] op_sel_hi:[1,0]
	v_pk_mul_f32 v[32:33], v[32:33], v[2:3] op_sel_hi:[1,0]
	v_pk_mul_f32 v[30:31], v[30:31], v[2:3] op_sel_hi:[1,0]
	v_pk_mul_f32 v[28:29], v[28:29], v[2:3] op_sel_hi:[1,0]
	v_pk_mul_f32 v[26:27], v[26:27], v[2:3] op_sel_hi:[1,0]
	v_pk_mul_f32 v[24:25], v[24:25], v[2:3] op_sel_hi:[1,0]
	v_pk_mul_f32 v[22:23], v[22:23], v[2:3] op_sel_hi:[1,0]
	v_pk_mul_f32 v[20:21], v[20:21], v[2:3] op_sel_hi:[1,0]
	v_pk_mul_f32 v[18:19], v[18:19], v[2:3] op_sel_hi:[1,0]
	v_pk_mul_f32 v[16:17], v[16:17], v[2:3] op_sel_hi:[1,0]

; DI void mla2_item(PP p, int item, unsigned char* lds) {
;     ...
;                 float mx = fmaxf(fmaxf(sc[0][0], sc[1][0]), fmaxf(sc[2][0], sc[3][0]));
; #pragma unroll
;                 for (int r = 1; r < 16; ++r) mx = fmaxf(mx, fmaxf(fmaxf(sc[0][r], sc[1][r]), fmaxf(sc[2][r], sc[3][r])));
;                 mx = fmaxf(mx, __shfl_xor(mx, 32));
;                 const float mnew = fmaxf(mrun, mx);
;                 const float alpha = __builtin_amdgcn_exp2f(mrun - mnew);
;                 float rsum = 0.f;
; #pragma unroll
;                 for (int kb = 0; kb < 4; ++kb)
; #pragma unroll
;                     for (int r = 0; r < 16; ++r) { sc[kb][r] = __builtin_amdgcn_exp2f(sc[kb][r] - mnew); rsum += sc[kb][r]; }
;                 const bool grew = mnew > mrun;
;                 lrun = lrun * alpha + rsum; mrun = mnew;
;                 if (__any(grew)) { o[0] = o[0] * alpha; o[1] = o[1] * alpha; }
.LBB0_290:
	s_or_b64 exec, exec, s[64:65]
	s_nop 3
	v_max3_f32 v1, v48, v49, v50
	v_max3_f32 v2, v80, v81, v82
	v_max3_f32 v3, v96, v97, v98
	v_max3_f32 v4, v64, v65, v66
	v_max3_f32 v1, v1, v51, v52
	v_max3_f32 v2, v2, v83, v84
	v_max3_f32 v3, v3, v99, v100
	v_max3_f32 v4, v4, v67, v68
	v_max3_f32 v1, v1, v53, v54
	v_max3_f32 v2, v2, v85, v86
	v_max3_f32 v3, v3, v101, v102
	v_max3_f32 v4, v4, v69, v70
	v_max3_f32 v1, v1, v55, v56
	v_max3_f32 v2, v2, v87, v88
	v_max3_f32 v3, v3, v103, v104
	v_max3_f32 v4, v4, v71, v72
	v_max3_f32 v1, v1, v57, v58
	v_max3_f32 v2, v2, v89, v90
	v_max3_f32 v3, v3, v105, v106
	v_max3_f32 v4, v4, v73, v74
	v_max3_f32 v1, v1, v59, v60
	v_max3_f32 v2, v2, v91, v92
	v_max3_f32 v3, v3, v107, v108
	v_max3_f32 v4, v4, v75, v76
	v_max3_f32 v1, v1, v61, v62
	v_max3_f32 v2, v2, v93, v94
	v_max3_f32 v3, v3, v109, v110
	v_max3_f32 v4, v4, v77, v78
	v_max_f32_e32 v1, v1, v63
	v_max_f32_e32 v2, v2, v95
	v_max_f32_e32 v3, v3, v111
	v_max_f32_e32 v4, v4, v79
	v_max3_f32 v1, v1, v2, v3
	v_max_f32_e32 v1, v1, v4
	v_mov_b32_e32 v2, v1
	s_nop 1
	v_permlane32_swap_b32_e32 v2, v1
	s_nop 0
	v_max3_f32 v1, v238, v1, v2
	v_sub_f32_e32 v2, v238, v1
	v_exp_f32_e32 v2, v2
	v_cmp_gt_f32_e32 vcc, v1, v238
	s_cbranch_vccz .LBB0_292
	v_pk_mul_f32 v[46:47], v[46:47], v[2:3] op_sel_hi:[1,0]
	v_pk_mul_f32 v[44:45], v[44:45], v[2:3] op_sel_hi:[1,0]
	v_pk_mul_f32 v[42:43], v[42:43], v[2:3] op_sel_hi:[1,0]
	v_pk_mul_f32 v[40:41], v[40:41], v[2:3] op_sel_hi:[1,0]
	v_pk_mul_f32 v[38:39], v[38:39], v[2:3] op_sel_hi:[1,0]
	v_pk_mul_f32 v[36:37], v[36:37], v[2:3] op_sel_hi:[1,0]
	v_pk_mul_f32 v[34:35], v[34:35], v[2:3] op_sel_hi:[1,0]
	v_pk_mul_f32 v[32:33], v[32:33], v[2:3] op_sel_hi:[1,0]
	v_pk_mul_f32 v[30:31], v[30:31], v[2:3] op_sel_hi:[1,0]
	v_pk_mul_f32 v[28:29], v[28:29], v[2:3] op_sel_hi:[1,0]
	v_pk_mul_f32 v[26:27], v[26:27], v[2:3] op_sel_hi:[1,0]
	v_pk_mul_f32 v[24:25], v[24:25], v[2:3] op_sel_hi:[1,0]
	v_pk_mul_f32 v[22:23], v[22:23], v[2:3] op_sel_hi:[1,0]
	v_pk_mul_f32 v[20:21], v[20:21], v[2:3] op_sel_hi:[1,0]
	v_pk_mul_f32 v[18:19], v[18:19], v[2:3] op_sel_hi:[1,0]
	v_pk_mul_f32 v[16:17], v[16:17], v[2:3] op_sel_hi:[1,0]

; DI void residual_store(PP p, int mt, int nt, const float* ct) {
;     ...
; #pragma unroll 1
;     for (int it = 0; it < 8; ++it) {
;         const int id = tid + 256 * it, row = id >> 4, cch = (id & 15) * 8;
;         float v[8]; ld8f(ct + row * CSTR + cch, v);
;         float* hp = p->h + (size_t)(row0 + row) * DM + col0 + cch;
;         float hv[8]; ld8f(hp, hv);
;         const bool pad = (lbase + row) < NPAD;
;         float ss = 0.f;
; #pragma unroll
;         for (int e = 0; e < 8; ++e) { v[e] = pad ? 0.f : (v[e] + hv[e]); ss += v[e] * v[e]; }
;         f32x4 o0 = {v[0], v[1], v[2], v[3]}, o1 = {v[4], v[5], v[6], v[7]};
;         *(f32x4*)hp = o0; *(f32x4*)(hp + 4) = o1;
;         *(bf16x8*)(p->hb + (size_t)(row0 + row) * DM + col0 + cch) = pack8(v[0], v[1], v[2], v[3], v[4], v[5], v[6], v[7]);
;         ss += __shfl_xor(ss, 1); ss += __shfl_xor(ss, 2); ss += __shfl_xor(ss, 4); ss += __shfl_xor(ss, 8);
;         if ((tid & 15) == 0) p->ssqh[(size_t)(row0 + row) * 8 + nt] = ss;
.LBB0_473:
	v_add_u32_e32 v74, s10, v80
	v_ashrrev_i32_e32 v75, 31, v74
	s_waitcnt lgkmcnt(0)
	v_lshlrev_b64 v[82:83], 12, v[74:75]
	v_lshl_add_u64 v[98:99], v[70:71], 0, v[82:83]
	global_load_dwordx4 v[82:85], v[98:99], off
	global_load_dwordx4 v[86:89], v[98:99], off offset:16
	v_add_u32_e32 v94, s3, v81
	ds_read_b128 v[90:93], v94
	v_or_b32_e32 v100, s2, v80
	ds_read_b128 v[94:97], v94 offset:16
	s_movk_i32 s0, 0x70
	v_cmp_gt_i32_e64 s[0:1], s0, v100
	s_waitcnt vmcnt(1) lgkmcnt(1)
	v_add_f32_e32 v83, v91, v83
	v_add_f32_e32 v82, v90, v82
	v_cndmask_b32_e64 v83, v83, 0, s[0:1]
	v_add_f32_e32 v84, v92, v84
	v_cndmask_b32_e64 v82, v82, 0, s[0:1]
	v_mul_f32_e32 v90, v83, v83
	v_add_f32_e32 v85, v93, v85
	v_cndmask_b32_e64 v84, v84, 0, s[0:1]
	v_fmac_f32_e32 v90, v82, v82
	s_waitcnt vmcnt(0) lgkmcnt(0)
	v_add_f32_e32 v86, v94, v86
	v_cndmask_b32_e64 v85, v85, 0, s[0:1]
	v_fmac_f32_e32 v90, v84, v84
	v_add_f32_e32 v87, v95, v87
	v_cndmask_b32_e64 v86, v86, 0, s[0:1]
	v_fmac_f32_e32 v90, v85, v85
	v_add_f32_e32 v88, v96, v88
	v_cndmask_b32_e64 v87, v87, 0, s[0:1]
	v_fmac_f32_e32 v90, v86, v86
	v_add_f32_e32 v89, v97, v89
	v_cndmask_b32_e64 v88, v88, 0, s[0:1]
	v_fmac_f32_e32 v90, v87, v87
	v_fmac_f32_e32 v90, v88, v88
	v_cndmask_b32_e64 v89, v89, 0, s[0:1]
	v_fmac_f32_e32 v90, v89, v89
	s_nop 1
	v_mov_b32_dpp v91, v90 quad_perm:[1,0,3,2] row_mask:0xf bank_mask:0xf
	global_store_dwordx4 v[98:99], v[82:85], off
	v_cvt_pk_bf16_f32 v92, v86, v87
	global_store_dwordx4 v[98:99], v[86:89], off offset:16
	s_waitcnt lgkmcnt(0)
	v_add_f32_e32 v90, v90, v91
	s_nop 1
	v_mov_b32_dpp v91, v90 quad_perm:[2,3,0,1] row_mask:0xf bank_mask:0xf
	s_waitcnt lgkmcnt(0)
	v_add_f32_e32 v93, v90, v91
	s_nop 1
	v_mov_b32_dpp v94, v93 row_half_mirror row_mask:0xf bank_mask:0xf
	v_cvt_pk_bf16_f32 v90, v82, v83
	v_cvt_pk_bf16_f32 v91, v84, v85
	v_lshlrev_b64 v[84:85], 11, v[74:75]
	v_lshl_add_u64 v[84:85], v[72:73], 0, v[84:85]
	s_waitcnt lgkmcnt(0)
	v_add_f32_e32 v82, v93, v94
	s_nop 1
	v_mov_b32_dpp v83, v82 row_mirror row_mask:0xf bank_mask:0xf
	v_cvt_pk_bf16_f32 v93, v88, v89
	global_store_dwordx4 v[84:85], v[90:93], off
	s_and_saveexec_b64 s[0:1], vcc
	s_cbranch_execz .LBB0_472
	s_load_dwordx2 s[4:5], s[82:83], 0x118
	v_lshlrev_b64 v[74:75], 5, v[74:75]
	s_waitcnt lgkmcnt(0)
	v_add_f32_e32 v82, v82, v83
	v_lshl_add_u64 v[74:75], s[4:5], 0, v[74:75]
	v_lshl_add_u64 v[74:75], v[130:131], 2, v[74:75]
	global_store_dword v[74:75], v82, off
	s_branch .LBB0_472

; DI void residual_store(PP p, int mt, int nt, const float* ct) {
;     ...
; #pragma unroll 1
;     for (int it = 0; it < 8; ++it) {
;         const int id = tid + 256 * it, row = id >> 4, cch = (id & 15) * 8;
;         float v[8]; ld8f(ct + row * CSTR + cch, v);
;         float* hp = p->h + (size_t)(row0 + row) * DM + col0 + cch;
;         float hv[8]; ld8f(hp, hv);
;         const bool pad = (lbase + row) < NPAD;
;         float ss = 0.f;
; #pragma unroll
;         for (int e = 0; e < 8; ++e) { v[e] = pad ? 0.f : (v[e] + hv[e]); ss += v[e] * v[e]; }
;         f32x4 o0 = {v[0], v[1], v[2], v[3]}, o1 = {v[4], v[5], v[6], v[7]};
;         *(f32x4*)hp = o0; *(f32x4*)(hp + 4) = o1;
;         *(bf16x8*)(p->hb + (size_t)(row0 + row) * DM + col0 + cch) = pack8(v[0], v[1], v[2], v[3], v[4], v[5], v[6], v[7]);
;         ss += __shfl_xor(ss, 1); ss += __shfl_xor(ss, 2); ss += __shfl_xor(ss, 4); ss += __shfl_xor(ss, 8);
;         if ((tid & 15) == 0) p->ssqh[(size_t)(row0 + row) * 8 + nt] = ss;
.LBB0_477:
	v_add_u32_e32 v6, s10, v8
	v_ashrrev_i32_e32 v7, 31, v6
	s_waitcnt lgkmcnt(0)
	v_lshlrev_b64 v[10:11], 12, v[6:7]
	v_lshl_add_u64 v[26:27], v[2:3], 0, v[10:11]
	global_load_dwordx4 v[10:13], v[26:27], off
	global_load_dwordx4 v[14:17], v[26:27], off offset:16
	v_add_u32_e32 v9, s3, v1
	ds_read_b128 v[18:21], v9
	ds_read_b128 v[22:25], v9 offset:16
	v_or_b32_e32 v28, s2, v8
	s_movk_i32 s0, 0x70
	v_cmp_gt_i32_e64 s[0:1], s0, v28
	s_waitcnt vmcnt(1) lgkmcnt(1)
	v_add_f32_e32 v11, v19, v11
	v_add_f32_e32 v9, v18, v10
	v_cndmask_b32_e64 v11, v11, 0, s[0:1]
	v_add_f32_e32 v12, v20, v12
	v_cndmask_b32_e64 v10, v9, 0, s[0:1]
	v_mul_f32_e32 v9, v11, v11
	v_add_f32_e32 v13, v21, v13
	v_cndmask_b32_e64 v12, v12, 0, s[0:1]
	v_fmac_f32_e32 v9, v10, v10
	s_waitcnt vmcnt(0) lgkmcnt(0)
	v_add_f32_e32 v14, v22, v14
	v_cndmask_b32_e64 v13, v13, 0, s[0:1]
	v_fmac_f32_e32 v9, v12, v12
	v_add_f32_e32 v15, v23, v15
	v_cndmask_b32_e64 v14, v14, 0, s[0:1]
	v_fmac_f32_e32 v9, v13, v13
	v_add_f32_e32 v16, v24, v16
	v_cndmask_b32_e64 v15, v15, 0, s[0:1]
	v_fmac_f32_e32 v9, v14, v14
	v_add_f32_e32 v17, v25, v17
	v_cndmask_b32_e64 v16, v16, 0, s[0:1]
	v_fmac_f32_e32 v9, v15, v15
	v_fmac_f32_e32 v9, v16, v16
	v_cndmask_b32_e64 v17, v17, 0, s[0:1]
	v_fmac_f32_e32 v9, v17, v17
	s_nop 1
	v_mov_b32_dpp v18, v9 quad_perm:[1,0,3,2] row_mask:0xf bank_mask:0xf
	global_store_dwordx4 v[26:27], v[10:13], off
	v_cvt_pk_bf16_f32 v19, v12, v13
	v_cvt_pk_bf16_f32 v20, v14, v15
	v_lshlrev_b64 v[12:13], 11, v[6:7]
	s_waitcnt lgkmcnt(0)
	v_add_f32_e32 v9, v9, v18
	s_nop 1
	v_mov_b32_dpp v18, v9 quad_perm:[2,3,0,1] row_mask:0xf bank_mask:0xf
	v_lshl_add_u64 v[12:13], v[4:5], 0, v[12:13]
	global_store_dwordx4 v[26:27], v[14:17], off offset:16
	s_waitcnt lgkmcnt(0)
	v_add_f32_e32 v9, v9, v18
	s_nop 1
	v_mov_b32_dpp v21, v9 row_half_mirror row_mask:0xf bank_mask:0xf
	v_cvt_pk_bf16_f32 v18, v10, v11
	s_waitcnt lgkmcnt(0)
	v_add_f32_e32 v9, v9, v21
	s_nop 1
	v_mov_b32_dpp v10, v9 row_mirror row_mask:0xf bank_mask:0xf
	v_cvt_pk_bf16_f32 v21, v16, v17
	global_store_dwordx4 v[12:13], v[18:21], off
	s_and_saveexec_b64 s[0:1], vcc
	s_cbranch_execz .LBB0_476
	s_load_dwordx2 s[4:5], s[82:83], 0x118
	v_lshlrev_b64 v[6:7], 5, v[6:7]
	s_waitcnt lgkmcnt(0)
	v_add_f32_e32 v9, v9, v10
	v_lshl_add_u64 v[6:7], s[4:5], 0, v[6:7]
	v_lshl_add_u64 v[6:7], v[130:131], 2, v[6:7]
	global_store_dword v[6:7], v9, off
	s_branch .LBB0_476

; DI void residual_store(PP p, int mt, int nt, const float* ct) {
;     ...
; #pragma unroll 1
;     for (int it = 0; it < 8; ++it) {
;         const int id = tid + 256 * it, row = id >> 4, cch = (id & 15) * 8;
;         float v[8]; ld8f(ct + row * CSTR + cch, v);
;         float* hp = p->h + (size_t)(row0 + row) * DM + col0 + cch;
;         float hv[8]; ld8f(hp, hv);
;         const bool pad = (lbase + row) < NPAD;
;         float ss = 0.f;
; #pragma unroll
;         for (int e = 0; e < 8; ++e) { v[e] = pad ? 0.f : (v[e] + hv[e]); ss += v[e] * v[e]; }
;         f32x4 o0 = {v[0], v[1], v[2], v[3]}, o1 = {v[4], v[5], v[6], v[7]};
;         *(f32x4*)hp = o0; *(f32x4*)(hp + 4) = o1;
;         *(bf16x8*)(p->hb + (size_t)(row0 + row) * DM + col0 + cch) = pack8(v[0], v[1], v[2], v[3], v[4], v[5], v[6], v[7]);
;         ss += __shfl_xor(ss, 1); ss += __shfl_xor(ss, 2); ss += __shfl_xor(ss, 4); ss += __shfl_xor(ss, 8);
;         if ((tid & 15) == 0) p->ssqh[(size_t)(row0 + row) * 8 + nt] = ss;
.LBB0_491:
	s_waitcnt lgkmcnt(0)
	global_load_dwordx4 v[78:81], v[70:71], off offset:-16
	global_load_dwordx4 v[82:85], v[70:71], off
	v_add_u32_e32 v77, s8, v76
	ds_read_b128 v[86:89], v77
	ds_read_b128 v[90:93], v77 offset:16
	v_or_b32_e32 v94, s7, v75
	s_movk_i32 s0, 0x70
	v_cmp_gt_u32_e64 s[0:1], s0, v94
	s_waitcnt vmcnt(1) lgkmcnt(1)
	v_add_f32_e32 v79, v87, v79
	v_add_f32_e32 v77, v86, v78
	v_cndmask_b32_e64 v79, v79, 0, s[0:1]
	v_add_f32_e32 v80, v88, v80
	v_cndmask_b32_e64 v78, v77, 0, s[0:1]
	v_mul_f32_e32 v77, v79, v79
	v_add_f32_e32 v81, v89, v81
	v_cndmask_b32_e64 v80, v80, 0, s[0:1]
	v_fmac_f32_e32 v77, v78, v78
	s_waitcnt vmcnt(0) lgkmcnt(0)
	v_add_f32_e32 v82, v90, v82
	v_cndmask_b32_e64 v81, v81, 0, s[0:1]
	v_fmac_f32_e32 v77, v80, v80
	v_add_f32_e32 v83, v91, v83
	v_cndmask_b32_e64 v82, v82, 0, s[0:1]
	v_fmac_f32_e32 v77, v81, v81
	v_add_f32_e32 v84, v92, v84
	v_cndmask_b32_e64 v83, v83, 0, s[0:1]
	v_fmac_f32_e32 v77, v82, v82
	v_add_f32_e32 v85, v93, v85
	v_cndmask_b32_e64 v84, v84, 0, s[0:1]
	v_fmac_f32_e32 v77, v83, v83
	v_fmac_f32_e32 v77, v84, v84
	v_cndmask_b32_e64 v85, v85, 0, s[0:1]
	v_fmac_f32_e32 v77, v85, v85
	s_nop 1
	v_mov_b32_dpp v86, v77 quad_perm:[1,0,3,2] row_mask:0xf bank_mask:0xf
	global_store_dwordx4 v[70:71], v[78:81], off offset:-16
	global_store_dwordx4 v[70:71], v[82:85], off
	v_cvt_pk_bf16_f32 v88, v82, v83
	v_cvt_pk_bf16_f32 v89, v84, v85
	s_waitcnt lgkmcnt(0)
	v_add_f32_e32 v77, v77, v86
	s_nop 1
	v_mov_b32_dpp v86, v77 quad_perm:[2,3,0,1] row_mask:0xf bank_mask:0xf
	s_waitcnt lgkmcnt(0)
	v_add_f32_e32 v77, v77, v86
	s_nop 1
	v_mov_b32_dpp v87, v77 row_half_mirror row_mask:0xf bank_mask:0xf
	v_cvt_pk_bf16_f32 v86, v78, v79
	s_waitcnt lgkmcnt(0)
	v_add_f32_e32 v77, v77, v87
	s_nop 1
	v_mov_b32_dpp v78, v77 row_mirror row_mask:0xf bank_mask:0xf
	v_cvt_pk_bf16_f32 v87, v80, v81
	global_store_dwordx4 v[68:69], v[86:89], off
	s_and_saveexec_b64 s[0:1], vcc
	s_cbranch_execz .LBB0_490
	s_load_dwordx2 s[10:11], s[82:83], 0x118
	s_waitcnt lgkmcnt(0)
	v_add_f32_e32 v77, v77, v78
	v_lshl_add_u64 v[78:79], s[10:11], 0, v[66:67]
	global_store_dword v[78:79], v77, off
	s_branch .LBB0_490

; DI void residual_store(PP p, int mt, int nt, const float* ct) {
;     ...
; #pragma unroll 1
;     for (int it = 0; it < 8; ++it) {
;         const int id = tid + 256 * it, row = id >> 4, cch = (id & 15) * 8;
;         float v[8]; ld8f(ct + row * CSTR + cch, v);
;         float* hp = p->h + (size_t)(row0 + row) * DM + col0 + cch;
;         float hv[8]; ld8f(hp, hv);
;         const bool pad = (lbase + row) < NPAD;
;         float ss = 0.f;
; #pragma unroll
;         for (int e = 0; e < 8; ++e) { v[e] = pad ? 0.f : (v[e] + hv[e]); ss += v[e] * v[e]; }
;         f32x4 o0 = {v[0], v[1], v[2], v[3]}, o1 = {v[4], v[5], v[6], v[7]};
;         *(f32x4*)hp = o0; *(f32x4*)(hp + 4) = o1;
;         *(bf16x8*)(p->hb + (size_t)(row0 + row) * DM + col0 + cch) = pack8(v[0], v[1], v[2], v[3], v[4], v[5], v[6], v[7]);
;         ss += __shfl_xor(ss, 1); ss += __shfl_xor(ss, 2); ss += __shfl_xor(ss, 4); ss += __shfl_xor(ss, 8);
;         if ((tid & 15) == 0) p->ssqh[(size_t)(row0 + row) * 8 + nt] = ss;
.LBB0_495:
	v_add_u32_e32 v196, s6, v6
	s_waitcnt lgkmcnt(0)
	v_lshlrev_b64 v[8:9], 12, v[196:197]
	v_lshl_add_u64 v[24:25], v[2:3], 0, v[8:9]
	global_load_dwordx4 v[8:11], v[24:25], off
	global_load_dwordx4 v[12:15], v[24:25], off offset:16
	v_add_u32_e32 v20, s3, v7
	ds_read_b128 v[16:19], v20
	v_or_b32_e32 v26, s2, v6
	ds_read_b128 v[20:23], v20 offset:16
	s_movk_i32 s0, 0x70
	v_cmp_gt_u32_e64 s[0:1], s0, v26
	s_waitcnt vmcnt(1) lgkmcnt(1)
	v_add_f32_e32 v9, v17, v9
	v_add_f32_e32 v8, v16, v8
	v_cndmask_b32_e64 v9, v9, 0, s[0:1]
	v_add_f32_e32 v10, v18, v10
	v_cndmask_b32_e64 v8, v8, 0, s[0:1]
	v_mul_f32_e32 v16, v9, v9
	v_add_f32_e32 v11, v19, v11
	v_cndmask_b32_e64 v10, v10, 0, s[0:1]
	v_fmac_f32_e32 v16, v8, v8
	s_waitcnt vmcnt(0) lgkmcnt(0)
	v_add_f32_e32 v12, v20, v12
	v_cndmask_b32_e64 v11, v11, 0, s[0:1]
	v_fmac_f32_e32 v16, v10, v10
	v_add_f32_e32 v13, v21, v13
	v_cndmask_b32_e64 v12, v12, 0, s[0:1]
	v_fmac_f32_e32 v16, v11, v11
	v_add_f32_e32 v14, v22, v14
	v_cndmask_b32_e64 v13, v13, 0, s[0:1]
	v_fmac_f32_e32 v16, v12, v12
	v_add_f32_e32 v15, v23, v15
	v_cndmask_b32_e64 v14, v14, 0, s[0:1]
	v_fmac_f32_e32 v16, v13, v13
	v_fmac_f32_e32 v16, v14, v14
	v_cndmask_b32_e64 v15, v15, 0, s[0:1]
	v_fmac_f32_e32 v16, v15, v15
	s_nop 1
	v_mov_b32_dpp v17, v16 quad_perm:[1,0,3,2] row_mask:0xf bank_mask:0xf
	global_store_dwordx4 v[24:25], v[8:11], off
	v_cvt_pk_bf16_f32 v18, v12, v13
	global_store_dwordx4 v[24:25], v[12:15], off offset:16
	s_waitcnt lgkmcnt(0)
	v_add_f32_e32 v16, v16, v17
	s_nop 1
	v_mov_b32_dpp v17, v16 quad_perm:[2,3,0,1] row_mask:0xf bank_mask:0xf
	s_waitcnt lgkmcnt(0)
	v_add_f32_e32 v19, v16, v17
	s_nop 1
	v_mov_b32_dpp v20, v19 row_half_mirror row_mask:0xf bank_mask:0xf
	v_cvt_pk_bf16_f32 v16, v8, v9
	v_cvt_pk_bf16_f32 v17, v10, v11
	v_lshlrev_b64 v[10:11], 11, v[196:197]
	v_lshl_add_u64 v[10:11], v[4:5], 0, v[10:11]
	s_waitcnt lgkmcnt(0)
	v_add_f32_e32 v8, v19, v20
	s_nop 1
	v_mov_b32_dpp v9, v8 row_mirror row_mask:0xf bank_mask:0xf
	v_cvt_pk_bf16_f32 v19, v14, v15
	global_store_dwordx4 v[10:11], v[16:19], off
	s_and_saveexec_b64 s[0:1], vcc
	s_cbranch_execz .LBB0_494
	s_load_dwordx2 s[4:5], s[82:83], 0x118
	s_waitcnt lgkmcnt(0)
	v_add_f32_e32 v10, v8, v9
	v_lshlrev_b64 v[8:9], 5, v[196:197]
	v_lshl_add_u64 v[8:9], s[4:5], 0, v[8:9]
	v_lshl_add_u64 v[8:9], v[130:131], 2, v[8:9]
	global_store_dword v[8:9], v10, off
	s_branch .LBB0_494
